# RMSNorm row sums: 64-lane xor butterflies through ds_bpermute replaced by DPP row adds + lane reads where the chain is contiguous (same additions, no LDS round trips)
# baseline (speedup 1.0000x reference)
.LBB0_98:
	v_ashrrev_i32_e32 v83, 31, v82
	v_lshlrev_b64 v[18:19], 12, v[82:83]
	v_lshl_add_u64 v[18:19], v[84:85], 0, v[18:19]
	global_load_dwordx4 v[78:81], v[18:19], off
	global_load_dwordx4 v[74:77], v[18:19], off offset:1024
	global_load_dwordx4 v[70:73], v[18:19], off offset:2048
	global_load_dwordx4 v[66:69], v[18:19], off offset:3072
	v_or_b32_e32 v92, 1, v82
	v_min_i32_e32 v18, 0x7fff, v92
	v_ashrrev_i32_e32 v19, 31, v18
	v_lshlrev_b64 v[18:19], 12, v[18:19]
	v_lshl_add_u64 v[18:19], v[84:85], 0, v[18:19]
	global_load_dwordx4 v[62:65], v[18:19], off
	global_load_dwordx4 v[58:61], v[18:19], off offset:1024
	global_load_dwordx4 v[54:57], v[18:19], off offset:2048
	global_load_dwordx4 v[50:53], v[18:19], off offset:3072
	v_or_b32_e32 v90, 2, v82
	v_min_i32_e32 v18, 0x7fff, v90
	v_ashrrev_i32_e32 v19, 31, v18
	v_lshlrev_b64 v[18:19], 12, v[18:19]
	v_lshl_add_u64 v[18:19], v[84:85], 0, v[18:19]
	v_or_b32_e32 v88, 3, v82
	global_load_dwordx4 v[46:49], v[18:19], off
	global_load_dwordx4 v[42:45], v[18:19], off offset:1024
	global_load_dwordx4 v[38:41], v[18:19], off offset:2048
	s_waitcnt lgkmcnt(0)
	global_load_dwordx4 v[34:37], v[18:19], off offset:3072
	v_min_i32_e32 v18, 0x7fff, v88
	v_ashrrev_i32_e32 v19, 31, v18
	v_lshlrev_b64 v[18:19], 12, v[18:19]
	v_lshl_add_u64 v[18:19], v[84:85], 0, v[18:19]
	global_load_dwordx4 v[30:33], v[18:19], off
	global_load_dwordx4 v[26:29], v[18:19], off offset:1024
	global_load_dwordx4 v[22:25], v[18:19], off offset:2048
	s_nop 0
	global_load_dwordx4 v[18:21], v[18:19], off offset:3072
	s_waitcnt vmcnt(0) lgkmcnt(0)
	v_pk_mul_f32 v[100:101], v[80:81], v[80:81]
	v_pk_mul_f32 v[102:103], v[78:79], v[78:79]
	v_mul_f32_e32 v16, v66, v66
	v_pk_mov_b32 v[104:105], v[102:103], v[100:101] op_sel:[1,0]
	v_mov_b32_e32 v103, v101
	v_pk_add_f32 v[100:101], v[104:105], v[102:103]
	v_pk_mul_f32 v[102:103], v[76:77], v[76:77]
	v_pk_mul_f32 v[104:105], v[74:75], v[74:75]
	v_mul_f32_e32 v89, v67, v67
	v_pk_mov_b32 v[106:107], v[104:105], v[102:103] op_sel:[1,0]
	v_mov_b32_e32 v105, v103
	v_pk_add_f32 v[102:103], v[106:107], v[104:105]
	v_pk_add_f32 v[100:101], v[100:101], v[100:101] op_sel:[0,1] op_sel_hi:[1,0]
	v_pk_add_f32 v[102:103], v[102:103], v[102:103] op_sel:[0,1] op_sel_hi:[1,0]
	v_mov_b32_e32 v101, v16
	v_mov_b32_e32 v103, v89
	v_mul_f32_e32 v16, v71, v71
	v_pk_add_f32 v[100:101], v[100:101], v[102:103]
	v_pk_fma_f32 v[102:103], v[70:71], v[70:71], v[16:17] op_sel_hi:[1,1,0]
	v_mul_f32_e32 v16, v73, v73
	v_mul_f32_e32 v91, v68, v68
	v_mul_f32_e32 v93, v69, v69
	v_pk_fma_f32 v[104:105], v[72:73], v[72:73], v[16:17] op_sel_hi:[1,1,0]
	v_mov_b32_e32 v103, v91
	v_mov_b32_e32 v105, v93
	v_pk_add_f32 v[102:103], v[102:103], v[104:105]
	s_nop 0
	v_pk_add_f32 v[100:101], v[100:101], v[102:103]
	s_nop 0
	v_add_f32_e32 v16, v100, v101
	v_lshlrev_b64 v[100:101], 11, v[82:83]
	v_lshl_add_u64 v[100:101], v[86:87], 0, v[100:101]
	s_nop 1
	v_add_f32_dpp v16, v16, v16 quad_perm:[1,0,3,2] row_mask:0xf bank_mask:0xf
	s_nop 1
	v_add_f32_dpp v16, v16, v16 quad_perm:[2,3,0,1] row_mask:0xf bank_mask:0xf
	s_nop 1
	v_add_f32_dpp v16, v16, v16 row_half_mirror row_mask:0xf bank_mask:0xf
	s_nop 1
	v_add_f32_dpp v16, v16, v16 row_mirror row_mask:0xf bank_mask:0xf
	s_nop 0
	v_readlane_b32 s98, v16, 0
	v_readlane_b32 s99, v16, 16
	v_readlane_b32 s100, v16, 32
	v_readlane_b32 s101, v16, 48
	v_mov_b32_e32 v89, s98
	v_add_f32_e32 v89, s99, v89
	v_mov_b32_e32 v16, s100
	v_add_f32_e32 v16, s101, v16
	v_add_f32_e32 v16, v89, v16
	v_fmamk_f32 v16, v16, 0x3a800000, v231
	v_cmp_gt_f32_e32 vcc, s33, v16
	v_mul_f32_e32 v83, 0x4b800000, v16
	s_nop 0
	v_cndmask_b32_e32 v16, v16, v83, vcc
	v_rsq_f32_e32 v16, v16
	s_nop 0
	v_mul_f32_e32 v83, 0x45800000, v16
	v_cndmask_b32_e32 v16, v16, v83, vcc
	v_mul_f32_e32 v78, v78, v16
	v_mul_f32_e32 v79, v79, v16
	v_mul_f32_e32 v74, v74, v16
	v_mul_f32_e32 v75, v75, v16
	v_mul_f32_e32 v70, v70, v16
	v_mul_f32_e32 v71, v71, v16
	v_mul_f32_e32 v66, v66, v16
	v_mul_f32_e32 v67, v67, v16
	v_mul_f32_e32 v78, v0, v78
	v_mul_f32_e32 v79, v1, v79
	v_mul_f32_e32 v74, v4, v74
	v_mul_f32_e32 v75, v5, v75
	v_mul_f32_e32 v70, v8, v70
	v_mul_f32_e32 v71, v9, v71
	v_mul_f32_e32 v66, v12, v66
	v_mul_f32_e32 v67, v13, v67
	v_cvt_pk_bf16_f32 v78, v78, v79
	v_mul_f32_e32 v79, v80, v16
	v_mul_f32_e32 v80, v81, v16
	v_cvt_pk_bf16_f32 v74, v74, v75
	v_mul_f32_e32 v75, v76, v16
	v_mul_f32_e32 v76, v77, v16
	v_cvt_pk_bf16_f32 v70, v70, v71
	v_mul_f32_e32 v71, v72, v16
	v_mul_f32_e32 v72, v73, v16
	v_cvt_pk_bf16_f32 v66, v66, v67
	v_mul_f32_e32 v67, v68, v16
	v_mul_f32_e32 v16, v69, v16
	v_mul_f32_e32 v67, v14, v67
	v_mul_f32_e32 v16, v15, v16
	v_cvt_pk_bf16_f32 v67, v67, v16
	global_store_dwordx2 v[100:101], v[66:67], off offset:1536
	v_mul_f32_e32 v16, v63, v63
	v_mul_f32_e32 v66, v65, v65
	v_fmac_f32_e32 v16, v62, v62
	v_fmac_f32_e32 v66, v64, v64
	v_add_f32_e32 v16, v16, v66
	v_mul_f32_e32 v66, v59, v59
	v_mul_f32_e32 v67, v61, v61
	v_fmac_f32_e32 v66, v58, v58
	v_fmac_f32_e32 v67, v60, v60
	v_add_f32_e32 v66, v66, v67
	v_add_f32_e32 v16, v16, v66
	v_mul_f32_e32 v66, v55, v55
	v_mul_f32_e32 v67, v57, v57
	v_fmac_f32_e32 v66, v54, v54
	v_fmac_f32_e32 v67, v56, v56
	v_add_f32_e32 v66, v66, v67
	v_add_f32_e32 v16, v16, v66
	v_mul_f32_e32 v66, v51, v51
	v_mul_f32_e32 v67, v53, v53
	v_fmac_f32_e32 v66, v50, v50
	v_fmac_f32_e32 v67, v52, v52
	v_add_f32_e32 v66, v66, v67
	v_add_f32_e32 v16, v16, v66
	ds_bpermute_b32 v66, v94, v16
	v_mul_f32_e32 v79, v2, v79
	v_mul_f32_e32 v75, v6, v75
	v_mul_f32_e32 v71, v10, v71
	v_cmp_gt_i32_e32 vcc, s47, v92
	s_waitcnt lgkmcnt(0)
	v_add_f32_e32 v16, v16, v66
	ds_bpermute_b32 v66, v95, v16
	v_mul_f32_e32 v80, v3, v80
	v_cvt_pk_bf16_f32 v79, v79, v80
	global_store_dwordx2 v[100:101], v[78:79], off
	v_mul_f32_e32 v76, v7, v76
	s_waitcnt lgkmcnt(0)
	v_add_f32_e32 v16, v16, v66
	ds_bpermute_b32 v66, v96, v16
	v_cvt_pk_bf16_f32 v75, v75, v76
	global_store_dwordx2 v[100:101], v[74:75], off offset:512
	v_mul_f32_e32 v72, v11, v72
	v_cvt_pk_bf16_f32 v71, v71, v72
	s_waitcnt lgkmcnt(0)
	v_add_f32_e32 v16, v16, v66
	ds_bpermute_b32 v66, v97, v16
	global_store_dwordx2 v[100:101], v[70:71], off offset:1024
	s_waitcnt lgkmcnt(0)
	v_add_f32_e32 v16, v16, v66
	ds_bpermute_b32 v66, v98, v16
	s_waitcnt lgkmcnt(0)
	v_add_f32_e32 v16, v16, v66
	ds_bpermute_b32 v66, v99, v16
	s_and_saveexec_b64 s[22:23], vcc
	s_cbranch_execz .LBB0_100
	s_waitcnt lgkmcnt(0)
	v_add_f32_e32 v16, v16, v66
	v_fmamk_f32 v16, v16, 0x3a800000, v231
	v_mul_f32_e32 v66, 0x4b800000, v16
	v_cmp_gt_f32_e32 vcc, s33, v16
	v_ashrrev_i32_e32 v93, 31, v92
	s_nop 0
	v_cndmask_b32_e32 v16, v16, v66, vcc
	v_rsq_f32_e32 v16, v16
	v_lshlrev_b64 v[66:67], 11, v[92:93]
	v_lshl_add_u64 v[66:67], v[86:87], 0, v[66:67]
	v_mul_f32_e32 v68, 0x45800000, v16
	v_cndmask_b32_e32 v16, v16, v68, vcc
	v_mul_f32_e32 v62, v62, v16
	v_mul_f32_e32 v63, v63, v16
	v_mul_f32_e32 v58, v58, v16
	v_mul_f32_e32 v59, v59, v16
	v_mul_f32_e32 v54, v54, v16
	v_mul_f32_e32 v55, v55, v16
	v_mul_f32_e32 v50, v50, v16
	v_mul_f32_e32 v51, v51, v16
	v_mul_f32_e32 v62, v0, v62
	v_mul_f32_e32 v63, v1, v63
	v_mul_f32_e32 v58, v4, v58
	v_mul_f32_e32 v59, v5, v59
	v_mul_f32_e32 v54, v8, v54
	v_mul_f32_e32 v55, v9, v55
	v_mul_f32_e32 v50, v12, v50
	v_mul_f32_e32 v51, v13, v51
	v_cvt_pk_bf16_f32 v62, v62, v63
	v_mul_f32_e32 v63, v64, v16
	v_cvt_pk_bf16_f32 v58, v58, v59
	v_mul_f32_e32 v59, v60, v16
	v_cvt_pk_bf16_f32 v54, v54, v55
	v_mul_f32_e32 v55, v56, v16
	v_cvt_pk_bf16_f32 v50, v50, v51
	v_mul_f32_e32 v51, v52, v16
	v_mul_f32_e32 v63, v2, v63
	v_mul_f32_e32 v64, v65, v16
	v_mul_f32_e32 v59, v6, v59
	v_mul_f32_e32 v60, v61, v16
	v_mul_f32_e32 v55, v10, v55
	v_mul_f32_e32 v56, v57, v16
	v_mul_f32_e32 v51, v14, v51
	v_mul_f32_e32 v16, v53, v16
	v_mul_f32_e32 v64, v3, v64
	v_cvt_pk_bf16_f32 v63, v63, v64
	global_store_dwordx2 v[66:67], v[62:63], off
	v_mul_f32_e32 v60, v7, v60
	v_cvt_pk_bf16_f32 v59, v59, v60
	global_store_dwordx2 v[66:67], v[58:59], off offset:512
	v_mul_f32_e32 v56, v11, v56
	v_cvt_pk_bf16_f32 v55, v55, v56
	global_store_dwordx2 v[66:67], v[54:55], off offset:1024
	v_mul_f32_e32 v16, v15, v16
	v_cvt_pk_bf16_f32 v51, v51, v16
	global_store_dwordx2 v[66:67], v[50:51], off offset:1536
.LBB0_100:
	s_or_b64 exec, exec, s[22:23]
	v_mul_f32_e32 v16, v47, v47
	v_mul_f32_e32 v50, v49, v49
	v_fmac_f32_e32 v16, v46, v46
	v_fmac_f32_e32 v50, v48, v48
	v_add_f32_e32 v16, v16, v50
	v_mul_f32_e32 v50, v43, v43
	v_mul_f32_e32 v51, v45, v45
	v_fmac_f32_e32 v50, v42, v42
	v_fmac_f32_e32 v51, v44, v44
	v_add_f32_e32 v50, v50, v51
	v_add_f32_e32 v16, v16, v50
	v_mul_f32_e32 v50, v39, v39
	v_mul_f32_e32 v51, v41, v41
	v_fmac_f32_e32 v50, v38, v38
	v_fmac_f32_e32 v51, v40, v40
	v_add_f32_e32 v50, v50, v51
	v_add_f32_e32 v16, v16, v50
	v_mul_f32_e32 v50, v35, v35
	v_mul_f32_e32 v51, v37, v37
	v_fmac_f32_e32 v50, v34, v34
	v_fmac_f32_e32 v51, v36, v36
	v_add_f32_e32 v50, v50, v51
	v_add_f32_e32 v16, v16, v50
	v_cmp_gt_i32_e32 vcc, s47, v90
	s_and_saveexec_b64 s[22:23], vcc
	s_cbranch_execz .LBB0_102
	s_nop 1
	v_add_f32_dpp v16, v16, v16 quad_perm:[1,0,3,2] row_mask:0xf bank_mask:0xf
	s_nop 1
	v_add_f32_dpp v16, v16, v16 quad_perm:[2,3,0,1] row_mask:0xf bank_mask:0xf
	s_nop 1
	v_add_f32_dpp v16, v16, v16 row_half_mirror row_mask:0xf bank_mask:0xf
	s_nop 1
	v_add_f32_dpp v16, v16, v16 row_mirror row_mask:0xf bank_mask:0xf
	s_nop 0
	v_readlane_b32 s98, v16, 0
	v_readlane_b32 s99, v16, 16
	v_readlane_b32 s100, v16, 32
	v_readlane_b32 s101, v16, 48
	v_mov_b32_e32 v50, s98
	v_add_f32_e32 v50, s99, v50
	v_mov_b32_e32 v16, s100
	v_add_f32_e32 v16, s101, v16
	v_add_f32_e32 v16, v50, v16
	v_fmamk_f32 v16, v16, 0x3a800000, v231
	v_mul_f32_e32 v50, 0x4b800000, v16
	v_cmp_gt_f32_e32 vcc, s33, v16
	v_ashrrev_i32_e32 v91, 31, v90
	s_nop 0
	v_cndmask_b32_e32 v16, v16, v50, vcc
	v_rsq_f32_e32 v16, v16
	v_lshlrev_b64 v[50:51], 11, v[90:91]
	v_lshl_add_u64 v[50:51], v[86:87], 0, v[50:51]
	v_mul_f32_e32 v52, 0x45800000, v16
	v_cndmask_b32_e32 v16, v16, v52, vcc
	v_mul_f32_e32 v46, v46, v16
	v_mul_f32_e32 v47, v47, v16
	v_mul_f32_e32 v42, v42, v16
	v_mul_f32_e32 v43, v43, v16
	v_mul_f32_e32 v38, v38, v16
	v_mul_f32_e32 v39, v39, v16
	v_mul_f32_e32 v34, v34, v16
	v_mul_f32_e32 v35, v35, v16
	v_mul_f32_e32 v46, v0, v46
	v_mul_f32_e32 v47, v1, v47
	v_mul_f32_e32 v42, v4, v42
	v_mul_f32_e32 v43, v5, v43
	v_mul_f32_e32 v38, v8, v38
	v_mul_f32_e32 v39, v9, v39
	v_mul_f32_e32 v34, v12, v34
	v_mul_f32_e32 v35, v13, v35
	v_cvt_pk_bf16_f32 v46, v46, v47
	v_mul_f32_e32 v47, v48, v16
	v_cvt_pk_bf16_f32 v42, v42, v43
	v_mul_f32_e32 v43, v44, v16
	v_cvt_pk_bf16_f32 v38, v38, v39
	v_mul_f32_e32 v39, v40, v16
	v_cvt_pk_bf16_f32 v34, v34, v35
	v_mul_f32_e32 v35, v36, v16
	v_mul_f32_e32 v47, v2, v47
	v_mul_f32_e32 v48, v49, v16
	v_mul_f32_e32 v43, v6, v43
	v_mul_f32_e32 v44, v45, v16
	v_mul_f32_e32 v39, v10, v39
	v_mul_f32_e32 v40, v41, v16
	v_mul_f32_e32 v35, v14, v35
	v_mul_f32_e32 v16, v37, v16
	v_mul_f32_e32 v48, v3, v48
	v_cvt_pk_bf16_f32 v47, v47, v48
	global_store_dwordx2 v[50:51], v[46:47], off
	v_mul_f32_e32 v44, v7, v44
	v_cvt_pk_bf16_f32 v43, v43, v44
	global_store_dwordx2 v[50:51], v[42:43], off offset:512
	v_mul_f32_e32 v40, v11, v40
	v_cvt_pk_bf16_f32 v39, v39, v40
	global_store_dwordx2 v[50:51], v[38:39], off offset:1024
	v_mul_f32_e32 v16, v15, v16
	v_cvt_pk_bf16_f32 v35, v35, v16
	global_store_dwordx2 v[50:51], v[34:35], off offset:1536
.LBB0_102:
	s_or_b64 exec, exec, s[22:23]
	v_mul_f32_e32 v16, v31, v31
	v_mul_f32_e32 v34, v33, v33
	v_fmac_f32_e32 v16, v30, v30
	v_fmac_f32_e32 v34, v32, v32
	v_add_f32_e32 v16, v16, v34
	v_mul_f32_e32 v34, v27, v27
	v_mul_f32_e32 v35, v29, v29
	v_fmac_f32_e32 v34, v26, v26
	v_fmac_f32_e32 v35, v28, v28
	v_add_f32_e32 v34, v34, v35
	v_add_f32_e32 v16, v16, v34
	v_mul_f32_e32 v34, v23, v23
	v_mul_f32_e32 v35, v25, v25
	v_fmac_f32_e32 v34, v22, v22
	v_fmac_f32_e32 v35, v24, v24
	v_add_f32_e32 v34, v34, v35
	v_add_f32_e32 v16, v16, v34
	v_mul_f32_e32 v34, v19, v19
	v_mul_f32_e32 v35, v21, v21
	v_fmac_f32_e32 v34, v18, v18
	v_fmac_f32_e32 v35, v20, v20
	v_add_f32_e32 v34, v34, v35
	v_add_f32_e32 v16, v16, v34
	v_cmp_gt_i32_e32 vcc, s47, v88
	s_and_saveexec_b64 s[22:23], vcc
	s_cbranch_execz .LBB0_97
	s_nop 1
	v_add_f32_dpp v16, v16, v16 quad_perm:[1,0,3,2] row_mask:0xf bank_mask:0xf
	s_nop 1
	v_add_f32_dpp v16, v16, v16 quad_perm:[2,3,0,1] row_mask:0xf bank_mask:0xf
	s_nop 1
	v_add_f32_dpp v16, v16, v16 row_half_mirror row_mask:0xf bank_mask:0xf
	s_nop 1
	v_add_f32_dpp v16, v16, v16 row_mirror row_mask:0xf bank_mask:0xf
	s_nop 0
	v_readlane_b32 s98, v16, 0
	v_readlane_b32 s99, v16, 16
	v_readlane_b32 s100, v16, 32
	v_readlane_b32 s101, v16, 48
	v_mov_b32_e32 v34, s98
	v_add_f32_e32 v34, s99, v34
	v_mov_b32_e32 v16, s100
	v_add_f32_e32 v16, s101, v16
	v_add_f32_e32 v16, v34, v16
	v_fmamk_f32 v16, v16, 0x3a800000, v231
	v_mul_f32_e32 v34, 0x4b800000, v16
	v_cmp_gt_f32_e32 vcc, s33, v16
	v_ashrrev_i32_e32 v89, 31, v88
	s_nop 0
	v_cndmask_b32_e32 v16, v16, v34, vcc
	v_rsq_f32_e32 v16, v16
	v_lshlrev_b64 v[34:35], 11, v[88:89]
	v_lshl_add_u64 v[34:35], v[86:87], 0, v[34:35]
	v_mul_f32_e32 v36, 0x45800000, v16
	v_cndmask_b32_e32 v16, v16, v36, vcc
	v_mul_f32_e32 v30, v30, v16
	v_mul_f32_e32 v31, v31, v16
	v_mul_f32_e32 v26, v26, v16
	v_mul_f32_e32 v27, v27, v16
	v_mul_f32_e32 v22, v22, v16
	v_mul_f32_e32 v23, v23, v16
	v_mul_f32_e32 v18, v18, v16
	v_mul_f32_e32 v19, v19, v16
	v_mul_f32_e32 v30, v0, v30
	v_mul_f32_e32 v31, v1, v31
	v_mul_f32_e32 v26, v4, v26
	v_mul_f32_e32 v27, v5, v27
	v_mul_f32_e32 v22, v8, v22
	v_mul_f32_e32 v23, v9, v23
	v_mul_f32_e32 v18, v12, v18
	v_mul_f32_e32 v19, v13, v19
	v_cvt_pk_bf16_f32 v30, v30, v31
	v_mul_f32_e32 v31, v32, v16
	v_cvt_pk_bf16_f32 v26, v26, v27
	v_mul_f32_e32 v27, v28, v16
	v_cvt_pk_bf16_f32 v22, v22, v23
	v_mul_f32_e32 v23, v24, v16
	v_cvt_pk_bf16_f32 v18, v18, v19
	v_mul_f32_e32 v19, v20, v16
	v_mul_f32_e32 v31, v2, v31
	v_mul_f32_e32 v32, v33, v16
	v_mul_f32_e32 v27, v6, v27
	v_mul_f32_e32 v28, v29, v16
	v_mul_f32_e32 v23, v10, v23
	v_mul_f32_e32 v24, v25, v16
	v_mul_f32_e32 v19, v14, v19
	v_mul_f32_e32 v16, v21, v16
	v_mul_f32_e32 v32, v3, v32
	v_cvt_pk_bf16_f32 v31, v31, v32
	global_store_dwordx2 v[34:35], v[30:31], off
	v_mul_f32_e32 v28, v7, v28
	v_cvt_pk_bf16_f32 v27, v27, v28
	global_store_dwordx2 v[34:35], v[26:27], off offset:512
	v_mul_f32_e32 v24, v11, v24
	v_cvt_pk_bf16_f32 v23, v23, v24
	global_store_dwordx2 v[34:35], v[22:23], off offset:1024
	v_mul_f32_e32 v16, v15, v16
	v_cvt_pk_bf16_f32 v19, v19, v16
	global_store_dwordx2 v[34:35], v[18:19], off offset:1536
	s_branch .LBB0_97

.LBB0_183:
	v_ashrrev_i32_e32 v83, 31, v82
	v_lshlrev_b64 v[18:19], 12, v[82:83]
	v_lshl_add_u64 v[18:19], v[84:85], 0, v[18:19]
	global_load_dwordx4 v[78:81], v[18:19], off
	global_load_dwordx4 v[74:77], v[18:19], off offset:1024
	global_load_dwordx4 v[70:73], v[18:19], off offset:2048
	global_load_dwordx4 v[66:69], v[18:19], off offset:3072
	v_or_b32_e32 v92, 1, v82
	v_min_i32_e32 v18, 0x3fff, v92
	v_ashrrev_i32_e32 v19, 31, v18
	v_lshlrev_b64 v[18:19], 12, v[18:19]
	v_lshl_add_u64 v[18:19], v[84:85], 0, v[18:19]
	global_load_dwordx4 v[62:65], v[18:19], off
	global_load_dwordx4 v[58:61], v[18:19], off offset:1024
	global_load_dwordx4 v[54:57], v[18:19], off offset:2048
	global_load_dwordx4 v[50:53], v[18:19], off offset:3072
	v_or_b32_e32 v90, 2, v82
	v_min_i32_e32 v18, 0x3fff, v90
	v_ashrrev_i32_e32 v19, 31, v18
	v_lshlrev_b64 v[18:19], 12, v[18:19]
	v_lshl_add_u64 v[18:19], v[84:85], 0, v[18:19]
	v_or_b32_e32 v88, 3, v82
	global_load_dwordx4 v[46:49], v[18:19], off
	global_load_dwordx4 v[42:45], v[18:19], off offset:1024
	global_load_dwordx4 v[38:41], v[18:19], off offset:2048
	s_waitcnt lgkmcnt(0)
	global_load_dwordx4 v[34:37], v[18:19], off offset:3072
	v_min_i32_e32 v18, 0x3fff, v88
	v_ashrrev_i32_e32 v19, 31, v18
	v_lshlrev_b64 v[18:19], 12, v[18:19]
	v_lshl_add_u64 v[18:19], v[84:85], 0, v[18:19]
	global_load_dwordx4 v[30:33], v[18:19], off
	global_load_dwordx4 v[26:29], v[18:19], off offset:1024
	global_load_dwordx4 v[22:25], v[18:19], off offset:2048
	s_nop 0
	global_load_dwordx4 v[18:21], v[18:19], off offset:3072
	s_waitcnt vmcnt(0) lgkmcnt(0)
	v_pk_mul_f32 v[100:101], v[80:81], v[80:81]
	v_pk_mul_f32 v[102:103], v[78:79], v[78:79]
	v_mul_f32_e32 v16, v66, v66
	v_pk_mov_b32 v[104:105], v[102:103], v[100:101] op_sel:[1,0]
	v_mov_b32_e32 v103, v101
	v_pk_add_f32 v[100:101], v[104:105], v[102:103]
	v_pk_mul_f32 v[102:103], v[76:77], v[76:77]
	v_pk_mul_f32 v[104:105], v[74:75], v[74:75]
	v_mul_f32_e32 v89, v67, v67
	v_pk_mov_b32 v[106:107], v[104:105], v[102:103] op_sel:[1,0]
	v_mov_b32_e32 v105, v103
	v_pk_add_f32 v[102:103], v[106:107], v[104:105]
	v_pk_add_f32 v[100:101], v[100:101], v[100:101] op_sel:[0,1] op_sel_hi:[1,0]
	v_pk_add_f32 v[102:103], v[102:103], v[102:103] op_sel:[0,1] op_sel_hi:[1,0]
	v_mov_b32_e32 v101, v16
	v_mov_b32_e32 v103, v89
	v_mul_f32_e32 v16, v71, v71
	v_pk_add_f32 v[100:101], v[100:101], v[102:103]
	v_pk_fma_f32 v[102:103], v[70:71], v[70:71], v[16:17] op_sel_hi:[1,1,0]
	v_mul_f32_e32 v16, v73, v73
	v_mul_f32_e32 v91, v68, v68
	v_mul_f32_e32 v93, v69, v69
	v_pk_fma_f32 v[104:105], v[72:73], v[72:73], v[16:17] op_sel_hi:[1,1,0]
	v_mov_b32_e32 v103, v91
	v_mov_b32_e32 v105, v93
	v_pk_add_f32 v[102:103], v[102:103], v[104:105]
	s_nop 0
	v_pk_add_f32 v[100:101], v[100:101], v[102:103]
	s_nop 0
	v_add_f32_e32 v16, v100, v101
	v_lshlrev_b64 v[100:101], 11, v[82:83]
	v_lshl_add_u64 v[100:101], v[86:87], 0, v[100:101]
	s_nop 1
	v_add_f32_dpp v16, v16, v16 quad_perm:[1,0,3,2] row_mask:0xf bank_mask:0xf
	s_nop 1
	v_add_f32_dpp v16, v16, v16 quad_perm:[2,3,0,1] row_mask:0xf bank_mask:0xf
	s_nop 1
	v_add_f32_dpp v16, v16, v16 row_half_mirror row_mask:0xf bank_mask:0xf
	s_nop 1
	v_add_f32_dpp v16, v16, v16 row_mirror row_mask:0xf bank_mask:0xf
	s_nop 0
	v_readlane_b32 s98, v16, 0
	v_readlane_b32 s99, v16, 16
	v_readlane_b32 s100, v16, 32
	v_readlane_b32 s101, v16, 48
	v_mov_b32_e32 v89, s98
	v_add_f32_e32 v89, s99, v89
	v_mov_b32_e32 v16, s100
	v_add_f32_e32 v16, s101, v16
	v_add_f32_e32 v16, v89, v16
	v_fmamk_f32 v16, v16, 0x3a800000, v231
	v_cmp_gt_f32_e32 vcc, s33, v16
	v_mul_f32_e32 v83, 0x4b800000, v16
	s_nop 0
	v_cndmask_b32_e32 v16, v16, v83, vcc
	v_rsq_f32_e32 v16, v16
	s_nop 0
	v_mul_f32_e32 v83, 0x45800000, v16
	v_cndmask_b32_e32 v16, v16, v83, vcc
	v_mul_f32_e32 v78, v78, v16
	v_mul_f32_e32 v79, v79, v16
	v_mul_f32_e32 v74, v74, v16
	v_mul_f32_e32 v75, v75, v16
	v_mul_f32_e32 v70, v70, v16
	v_mul_f32_e32 v71, v71, v16
	v_mul_f32_e32 v66, v66, v16
	v_mul_f32_e32 v67, v67, v16
	v_mul_f32_e32 v78, v0, v78
	v_mul_f32_e32 v79, v1, v79
	v_mul_f32_e32 v74, v4, v74
	v_mul_f32_e32 v75, v5, v75
	v_mul_f32_e32 v70, v8, v70
	v_mul_f32_e32 v71, v9, v71
	v_mul_f32_e32 v66, v12, v66
	v_mul_f32_e32 v67, v13, v67
	v_cvt_pk_bf16_f32 v78, v78, v79
	v_mul_f32_e32 v79, v80, v16
	v_mul_f32_e32 v80, v81, v16
	v_cvt_pk_bf16_f32 v74, v74, v75
	v_mul_f32_e32 v75, v76, v16
	v_mul_f32_e32 v76, v77, v16
	v_cvt_pk_bf16_f32 v70, v70, v71
	v_mul_f32_e32 v71, v72, v16
	v_mul_f32_e32 v72, v73, v16
	v_cvt_pk_bf16_f32 v66, v66, v67
	v_mul_f32_e32 v67, v68, v16
	v_mul_f32_e32 v16, v69, v16
	v_mul_f32_e32 v67, v14, v67
	v_mul_f32_e32 v16, v15, v16
	v_cvt_pk_bf16_f32 v67, v67, v16
	global_store_dwordx2 v[100:101], v[66:67], off offset:1536
	v_mul_f32_e32 v16, v63, v63
	v_mul_f32_e32 v66, v65, v65
	v_fmac_f32_e32 v16, v62, v62
	v_fmac_f32_e32 v66, v64, v64
	v_add_f32_e32 v16, v16, v66
	v_mul_f32_e32 v66, v59, v59
	v_mul_f32_e32 v67, v61, v61
	v_fmac_f32_e32 v66, v58, v58
	v_fmac_f32_e32 v67, v60, v60
	v_add_f32_e32 v66, v66, v67
	v_add_f32_e32 v16, v16, v66
	v_mul_f32_e32 v66, v55, v55
	v_mul_f32_e32 v67, v57, v57
	v_fmac_f32_e32 v66, v54, v54
	v_fmac_f32_e32 v67, v56, v56
	v_add_f32_e32 v66, v66, v67
	v_add_f32_e32 v16, v16, v66
	v_mul_f32_e32 v66, v51, v51
	v_mul_f32_e32 v67, v53, v53
	v_fmac_f32_e32 v66, v50, v50
	v_fmac_f32_e32 v67, v52, v52
	v_add_f32_e32 v66, v66, v67
	v_add_f32_e32 v16, v16, v66
	ds_bpermute_b32 v66, v94, v16
	v_mul_f32_e32 v79, v2, v79
	v_mul_f32_e32 v75, v6, v75
	v_mul_f32_e32 v71, v10, v71
	v_cmp_gt_i32_e32 vcc, s62, v92
	s_waitcnt lgkmcnt(0)
	v_add_f32_e32 v16, v16, v66
	ds_bpermute_b32 v66, v95, v16
	v_mul_f32_e32 v80, v3, v80
	v_cvt_pk_bf16_f32 v79, v79, v80
	global_store_dwordx2 v[100:101], v[78:79], off
	v_mul_f32_e32 v76, v7, v76
	s_waitcnt lgkmcnt(0)
	v_add_f32_e32 v16, v16, v66
	ds_bpermute_b32 v66, v96, v16
	v_cvt_pk_bf16_f32 v75, v75, v76
	global_store_dwordx2 v[100:101], v[74:75], off offset:512
	v_mul_f32_e32 v72, v11, v72
	v_cvt_pk_bf16_f32 v71, v71, v72
	s_waitcnt lgkmcnt(0)
	v_add_f32_e32 v16, v16, v66
	ds_bpermute_b32 v66, v97, v16
	global_store_dwordx2 v[100:101], v[70:71], off offset:1024
	s_waitcnt lgkmcnt(0)
	v_add_f32_e32 v16, v16, v66
	ds_bpermute_b32 v66, v98, v16
	s_waitcnt lgkmcnt(0)
	v_add_f32_e32 v16, v16, v66
	ds_bpermute_b32 v66, v99, v16
	s_and_saveexec_b64 s[14:15], vcc
	s_cbranch_execz .LBB0_185
	s_waitcnt lgkmcnt(0)
	v_add_f32_e32 v16, v16, v66
	v_fmamk_f32 v16, v16, 0x3a800000, v231
	v_mul_f32_e32 v66, 0x4b800000, v16
	v_cmp_gt_f32_e32 vcc, s33, v16
	v_ashrrev_i32_e32 v93, 31, v92
	s_nop 0
	v_cndmask_b32_e32 v16, v16, v66, vcc
	v_rsq_f32_e32 v16, v16
	v_lshlrev_b64 v[66:67], 11, v[92:93]
	v_lshl_add_u64 v[66:67], v[86:87], 0, v[66:67]
	v_mul_f32_e32 v68, 0x45800000, v16
	v_cndmask_b32_e32 v16, v16, v68, vcc
	v_mul_f32_e32 v62, v62, v16
	v_mul_f32_e32 v63, v63, v16
	v_mul_f32_e32 v58, v58, v16
	v_mul_f32_e32 v59, v59, v16
	v_mul_f32_e32 v54, v54, v16
	v_mul_f32_e32 v55, v55, v16
	v_mul_f32_e32 v50, v50, v16
	v_mul_f32_e32 v51, v51, v16
	v_mul_f32_e32 v62, v0, v62
	v_mul_f32_e32 v63, v1, v63
	v_mul_f32_e32 v58, v4, v58
	v_mul_f32_e32 v59, v5, v59
	v_mul_f32_e32 v54, v8, v54
	v_mul_f32_e32 v55, v9, v55
	v_mul_f32_e32 v50, v12, v50
	v_mul_f32_e32 v51, v13, v51
	v_cvt_pk_bf16_f32 v62, v62, v63
	v_mul_f32_e32 v63, v64, v16
	v_cvt_pk_bf16_f32 v58, v58, v59
	v_mul_f32_e32 v59, v60, v16
	v_cvt_pk_bf16_f32 v54, v54, v55
	v_mul_f32_e32 v55, v56, v16
	v_cvt_pk_bf16_f32 v50, v50, v51
	v_mul_f32_e32 v51, v52, v16
	v_mul_f32_e32 v63, v2, v63
	v_mul_f32_e32 v64, v65, v16
	v_mul_f32_e32 v59, v6, v59
	v_mul_f32_e32 v60, v61, v16
	v_mul_f32_e32 v55, v10, v55
	v_mul_f32_e32 v56, v57, v16
	v_mul_f32_e32 v51, v14, v51
	v_mul_f32_e32 v16, v53, v16
	v_mul_f32_e32 v64, v3, v64
	v_cvt_pk_bf16_f32 v63, v63, v64
	global_store_dwordx2 v[66:67], v[62:63], off
	v_mul_f32_e32 v60, v7, v60
	v_cvt_pk_bf16_f32 v59, v59, v60
	global_store_dwordx2 v[66:67], v[58:59], off offset:512
	v_mul_f32_e32 v56, v11, v56
	v_cvt_pk_bf16_f32 v55, v55, v56
	global_store_dwordx2 v[66:67], v[54:55], off offset:1024
	v_mul_f32_e32 v16, v15, v16
	v_cvt_pk_bf16_f32 v51, v51, v16
	global_store_dwordx2 v[66:67], v[50:51], off offset:1536
.LBB0_185:
	s_or_b64 exec, exec, s[14:15]
	v_mul_f32_e32 v16, v47, v47
	v_mul_f32_e32 v50, v49, v49
	v_fmac_f32_e32 v16, v46, v46
	v_fmac_f32_e32 v50, v48, v48
	v_add_f32_e32 v16, v16, v50
	v_mul_f32_e32 v50, v43, v43
	v_mul_f32_e32 v51, v45, v45
	v_fmac_f32_e32 v50, v42, v42
	v_fmac_f32_e32 v51, v44, v44
	v_add_f32_e32 v50, v50, v51
	v_add_f32_e32 v16, v16, v50
	v_mul_f32_e32 v50, v39, v39
	v_mul_f32_e32 v51, v41, v41
	v_fmac_f32_e32 v50, v38, v38
	v_fmac_f32_e32 v51, v40, v40
	v_add_f32_e32 v50, v50, v51
	v_add_f32_e32 v16, v16, v50
	v_mul_f32_e32 v50, v35, v35
	v_mul_f32_e32 v51, v37, v37
	v_fmac_f32_e32 v50, v34, v34
	v_fmac_f32_e32 v51, v36, v36
	v_add_f32_e32 v50, v50, v51
	v_add_f32_e32 v16, v16, v50
	v_cmp_gt_i32_e32 vcc, s62, v90
	s_and_saveexec_b64 s[14:15], vcc
	s_cbranch_execz .LBB0_187
	s_nop 1
	v_add_f32_dpp v16, v16, v16 quad_perm:[1,0,3,2] row_mask:0xf bank_mask:0xf
	s_nop 1
	v_add_f32_dpp v16, v16, v16 quad_perm:[2,3,0,1] row_mask:0xf bank_mask:0xf
	s_nop 1
	v_add_f32_dpp v16, v16, v16 row_half_mirror row_mask:0xf bank_mask:0xf
	s_nop 1
	v_add_f32_dpp v16, v16, v16 row_mirror row_mask:0xf bank_mask:0xf
	s_nop 0
	v_readlane_b32 s98, v16, 0
	v_readlane_b32 s99, v16, 16
	v_readlane_b32 s100, v16, 32
	v_readlane_b32 s101, v16, 48
	v_mov_b32_e32 v50, s98
	v_add_f32_e32 v50, s99, v50
	v_mov_b32_e32 v16, s100
	v_add_f32_e32 v16, s101, v16
	v_add_f32_e32 v16, v50, v16
	v_fmamk_f32 v16, v16, 0x3a800000, v231
	v_mul_f32_e32 v50, 0x4b800000, v16
	v_cmp_gt_f32_e32 vcc, s33, v16
	v_ashrrev_i32_e32 v91, 31, v90
	s_nop 0
	v_cndmask_b32_e32 v16, v16, v50, vcc
	v_rsq_f32_e32 v16, v16
	v_lshlrev_b64 v[50:51], 11, v[90:91]
	v_lshl_add_u64 v[50:51], v[86:87], 0, v[50:51]
	v_mul_f32_e32 v52, 0x45800000, v16
	v_cndmask_b32_e32 v16, v16, v52, vcc
	v_mul_f32_e32 v46, v46, v16
	v_mul_f32_e32 v47, v47, v16
	v_mul_f32_e32 v42, v42, v16
	v_mul_f32_e32 v43, v43, v16
	v_mul_f32_e32 v38, v38, v16
	v_mul_f32_e32 v39, v39, v16
	v_mul_f32_e32 v34, v34, v16
	v_mul_f32_e32 v35, v35, v16
	v_mul_f32_e32 v46, v0, v46
	v_mul_f32_e32 v47, v1, v47
	v_mul_f32_e32 v42, v4, v42
	v_mul_f32_e32 v43, v5, v43
	v_mul_f32_e32 v38, v8, v38
	v_mul_f32_e32 v39, v9, v39
	v_mul_f32_e32 v34, v12, v34
	v_mul_f32_e32 v35, v13, v35
	v_cvt_pk_bf16_f32 v46, v46, v47
	v_mul_f32_e32 v47, v48, v16
	v_cvt_pk_bf16_f32 v42, v42, v43
	v_mul_f32_e32 v43, v44, v16
	v_cvt_pk_bf16_f32 v38, v38, v39
	v_mul_f32_e32 v39, v40, v16
	v_cvt_pk_bf16_f32 v34, v34, v35
	v_mul_f32_e32 v35, v36, v16
	v_mul_f32_e32 v47, v2, v47
	v_mul_f32_e32 v48, v49, v16
	v_mul_f32_e32 v43, v6, v43
	v_mul_f32_e32 v44, v45, v16
	v_mul_f32_e32 v39, v10, v39
	v_mul_f32_e32 v40, v41, v16
	v_mul_f32_e32 v35, v14, v35
	v_mul_f32_e32 v16, v37, v16
	v_mul_f32_e32 v48, v3, v48
	v_cvt_pk_bf16_f32 v47, v47, v48
	global_store_dwordx2 v[50:51], v[46:47], off
	v_mul_f32_e32 v44, v7, v44
	v_cvt_pk_bf16_f32 v43, v43, v44
	global_store_dwordx2 v[50:51], v[42:43], off offset:512
	v_mul_f32_e32 v40, v11, v40
	v_cvt_pk_bf16_f32 v39, v39, v40
	global_store_dwordx2 v[50:51], v[38:39], off offset:1024
	v_mul_f32_e32 v16, v15, v16
	v_cvt_pk_bf16_f32 v35, v35, v16
	global_store_dwordx2 v[50:51], v[34:35], off offset:1536
.LBB0_187:
	s_or_b64 exec, exec, s[14:15]
	v_mul_f32_e32 v16, v31, v31
	v_mul_f32_e32 v34, v33, v33
	v_fmac_f32_e32 v16, v30, v30
	v_fmac_f32_e32 v34, v32, v32
	v_add_f32_e32 v16, v16, v34
	v_mul_f32_e32 v34, v27, v27
	v_mul_f32_e32 v35, v29, v29
	v_fmac_f32_e32 v34, v26, v26
	v_fmac_f32_e32 v35, v28, v28
	v_add_f32_e32 v34, v34, v35
	v_add_f32_e32 v16, v16, v34
	v_mul_f32_e32 v34, v23, v23
	v_mul_f32_e32 v35, v25, v25
	v_fmac_f32_e32 v34, v22, v22
	v_fmac_f32_e32 v35, v24, v24
	v_add_f32_e32 v34, v34, v35
	v_add_f32_e32 v16, v16, v34
	v_mul_f32_e32 v34, v19, v19
	v_mul_f32_e32 v35, v21, v21
	v_fmac_f32_e32 v34, v18, v18
	v_fmac_f32_e32 v35, v20, v20
	v_add_f32_e32 v34, v34, v35
	v_add_f32_e32 v16, v16, v34
	v_cmp_gt_i32_e32 vcc, s62, v88
	s_and_saveexec_b64 s[14:15], vcc
	s_cbranch_execz .LBB0_182
	s_nop 1
	v_add_f32_dpp v16, v16, v16 quad_perm:[1,0,3,2] row_mask:0xf bank_mask:0xf
	s_nop 1
	v_add_f32_dpp v16, v16, v16 quad_perm:[2,3,0,1] row_mask:0xf bank_mask:0xf
	s_nop 1
	v_add_f32_dpp v16, v16, v16 row_half_mirror row_mask:0xf bank_mask:0xf
	s_nop 1
	v_add_f32_dpp v16, v16, v16 row_mirror row_mask:0xf bank_mask:0xf
	s_nop 0
	v_readlane_b32 s98, v16, 0
	v_readlane_b32 s99, v16, 16
	v_readlane_b32 s100, v16, 32
	v_readlane_b32 s101, v16, 48
	v_mov_b32_e32 v34, s98
	v_add_f32_e32 v34, s99, v34
	v_mov_b32_e32 v16, s100
	v_add_f32_e32 v16, s101, v16
	v_add_f32_e32 v16, v34, v16
	v_fmamk_f32 v16, v16, 0x3a800000, v231
	v_mul_f32_e32 v34, 0x4b800000, v16
	v_cmp_gt_f32_e32 vcc, s33, v16
	v_ashrrev_i32_e32 v89, 31, v88
	s_nop 0
	v_cndmask_b32_e32 v16, v16, v34, vcc
	v_rsq_f32_e32 v16, v16
	v_lshlrev_b64 v[34:35], 11, v[88:89]
	v_lshl_add_u64 v[34:35], v[86:87], 0, v[34:35]
	v_mul_f32_e32 v36, 0x45800000, v16
	v_cndmask_b32_e32 v16, v16, v36, vcc
	v_mul_f32_e32 v30, v30, v16
	v_mul_f32_e32 v31, v31, v16
	v_mul_f32_e32 v26, v26, v16
	v_mul_f32_e32 v27, v27, v16
	v_mul_f32_e32 v22, v22, v16
	v_mul_f32_e32 v23, v23, v16
	v_mul_f32_e32 v18, v18, v16
	v_mul_f32_e32 v19, v19, v16
	v_mul_f32_e32 v30, v0, v30
	v_mul_f32_e32 v31, v1, v31
	v_mul_f32_e32 v26, v4, v26
	v_mul_f32_e32 v27, v5, v27
	v_mul_f32_e32 v22, v8, v22
	v_mul_f32_e32 v23, v9, v23
	v_mul_f32_e32 v18, v12, v18
	v_mul_f32_e32 v19, v13, v19
	v_cvt_pk_bf16_f32 v30, v30, v31
	v_mul_f32_e32 v31, v32, v16
	v_cvt_pk_bf16_f32 v26, v26, v27
	v_mul_f32_e32 v27, v28, v16
	v_cvt_pk_bf16_f32 v22, v22, v23
	v_mul_f32_e32 v23, v24, v16
	v_cvt_pk_bf16_f32 v18, v18, v19
	v_mul_f32_e32 v19, v20, v16
	v_mul_f32_e32 v31, v2, v31
	v_mul_f32_e32 v32, v33, v16
	v_mul_f32_e32 v27, v6, v27
	v_mul_f32_e32 v28, v29, v16
	v_mul_f32_e32 v23, v10, v23
	v_mul_f32_e32 v24, v25, v16
	v_mul_f32_e32 v19, v14, v19
	v_mul_f32_e32 v16, v21, v16
	v_mul_f32_e32 v32, v3, v32
	v_cvt_pk_bf16_f32 v31, v31, v32
	global_store_dwordx2 v[34:35], v[30:31], off
	v_mul_f32_e32 v28, v7, v28
	v_cvt_pk_bf16_f32 v27, v27, v28
	global_store_dwordx2 v[34:35], v[26:27], off offset:512
	v_mul_f32_e32 v24, v11, v24
	v_cvt_pk_bf16_f32 v23, v23, v24
	global_store_dwordx2 v[34:35], v[22:23], off offset:1024
	v_mul_f32_e32 v16, v15, v16
	v_cvt_pk_bf16_f32 v19, v19, v16
	global_store_dwordx2 v[34:35], v[18:19], off offset:1536
	s_branch .LBB0_182

.LBB0_1152:
	s_or_b64 exec, exec, s[12:13]
	v_mul_f32_e32 v16, v47, v47
	v_mul_f32_e32 v50, v49, v49
	v_fmac_f32_e32 v16, v46, v46
	v_fmac_f32_e32 v50, v48, v48
	v_add_f32_e32 v16, v16, v50
	v_mul_f32_e32 v50, v43, v43
	v_mul_f32_e32 v51, v45, v45
	v_fmac_f32_e32 v50, v42, v42
	v_fmac_f32_e32 v51, v44, v44
	v_add_f32_e32 v50, v50, v51
	v_add_f32_e32 v16, v16, v50
	v_mul_f32_e32 v50, v39, v39
	v_mul_f32_e32 v51, v41, v41
	v_fmac_f32_e32 v50, v38, v38
	v_fmac_f32_e32 v51, v40, v40
	v_add_f32_e32 v50, v50, v51
	v_add_f32_e32 v16, v16, v50
	v_mul_f32_e32 v50, v35, v35
	v_mul_f32_e32 v51, v37, v37
	v_fmac_f32_e32 v50, v34, v34
	v_fmac_f32_e32 v51, v36, v36
	v_add_f32_e32 v50, v50, v51
	v_add_f32_e32 v16, v16, v50
	v_cmp_gt_i32_e32 vcc, s47, v82
	s_and_saveexec_b64 s[12:13], vcc
	s_cbranch_execz .LBB0_1154
	s_nop 1
	v_add_f32_dpp v16, v16, v16 quad_perm:[1,0,3,2] row_mask:0xf bank_mask:0xf
	s_nop 1
	v_add_f32_dpp v16, v16, v16 quad_perm:[2,3,0,1] row_mask:0xf bank_mask:0xf
	s_nop 1
	v_add_f32_dpp v16, v16, v16 row_half_mirror row_mask:0xf bank_mask:0xf
	s_nop 1
	v_add_f32_dpp v16, v16, v16 row_mirror row_mask:0xf bank_mask:0xf
	s_nop 0
	v_readlane_b32 s98, v16, 0
	v_readlane_b32 s99, v16, 16
	v_readlane_b32 s100, v16, 32
	v_readlane_b32 s101, v16, 48
	v_mov_b32_e32 v50, s98
	v_add_f32_e32 v50, s99, v50
	v_mov_b32_e32 v16, s100
	v_add_f32_e32 v16, s101, v16
	v_add_f32_e32 v16, v50, v16
	v_fmamk_f32 v16, v16, 0x3a800000, v231
	v_mul_f32_e32 v50, 0x4b800000, v16
	v_cmp_gt_f32_e32 vcc, s33, v16
	v_ashrrev_i32_e32 v83, 31, v82
	s_nop 0
	v_cndmask_b32_e32 v16, v16, v50, vcc
	v_rsq_f32_e32 v16, v16
	v_lshlrev_b64 v[50:51], 11, v[82:83]
	v_lshl_add_u64 v[50:51], v[78:79], 0, v[50:51]
	v_mul_f32_e32 v52, 0x45800000, v16
	v_cndmask_b32_e32 v16, v16, v52, vcc
	v_mul_f32_e32 v46, v46, v16
	v_mul_f32_e32 v47, v47, v16
	v_mul_f32_e32 v42, v42, v16
	v_mul_f32_e32 v43, v43, v16
	v_mul_f32_e32 v38, v38, v16
	v_mul_f32_e32 v39, v39, v16
	v_mul_f32_e32 v34, v34, v16
	v_mul_f32_e32 v35, v35, v16
	v_mul_f32_e32 v46, v0, v46
	v_mul_f32_e32 v47, v1, v47
	v_mul_f32_e32 v42, v4, v42
	v_mul_f32_e32 v43, v5, v43
	v_mul_f32_e32 v38, v8, v38
	v_mul_f32_e32 v39, v9, v39
	v_mul_f32_e32 v34, v12, v34
	v_mul_f32_e32 v35, v13, v35
	v_cvt_pk_bf16_f32 v46, v46, v47
	v_mul_f32_e32 v47, v48, v16
	v_cvt_pk_bf16_f32 v42, v42, v43
	v_mul_f32_e32 v43, v44, v16
	v_cvt_pk_bf16_f32 v38, v38, v39
	v_mul_f32_e32 v39, v40, v16
	v_cvt_pk_bf16_f32 v34, v34, v35
	v_mul_f32_e32 v35, v36, v16
	v_mul_f32_e32 v47, v2, v47
	v_mul_f32_e32 v48, v49, v16
	v_mul_f32_e32 v43, v6, v43
	v_mul_f32_e32 v44, v45, v16
	v_mul_f32_e32 v39, v10, v39
	v_mul_f32_e32 v40, v41, v16
	v_mul_f32_e32 v35, v14, v35
	v_mul_f32_e32 v16, v37, v16
	v_mul_f32_e32 v48, v3, v48
	v_cvt_pk_bf16_f32 v47, v47, v48
	global_store_dwordx2 v[50:51], v[46:47], off
	v_mul_f32_e32 v44, v7, v44
	v_cvt_pk_bf16_f32 v43, v43, v44
	global_store_dwordx2 v[50:51], v[42:43], off offset:512
	v_mul_f32_e32 v40, v11, v40
	v_cvt_pk_bf16_f32 v39, v39, v40
	global_store_dwordx2 v[50:51], v[38:39], off offset:1024
	v_mul_f32_e32 v16, v15, v16
	v_cvt_pk_bf16_f32 v35, v35, v16
	global_store_dwordx2 v[50:51], v[34:35], off offset:1536
.LBB0_1154:
	s_or_b64 exec, exec, s[12:13]
	v_mul_f32_e32 v16, v31, v31
	v_mul_f32_e32 v34, v33, v33
	v_fmac_f32_e32 v16, v30, v30
	v_fmac_f32_e32 v34, v32, v32
	v_add_f32_e32 v16, v16, v34
	v_mul_f32_e32 v34, v27, v27
	v_mul_f32_e32 v35, v29, v29
	v_fmac_f32_e32 v34, v26, v26
	v_fmac_f32_e32 v35, v28, v28
	v_add_f32_e32 v34, v34, v35
	v_add_f32_e32 v16, v16, v34
	v_mul_f32_e32 v34, v23, v23
	v_mul_f32_e32 v35, v25, v25
	v_fmac_f32_e32 v34, v22, v22
	v_fmac_f32_e32 v35, v24, v24
	v_add_f32_e32 v34, v34, v35
	v_add_f32_e32 v16, v16, v34
	v_mul_f32_e32 v34, v19, v19
	v_mul_f32_e32 v35, v21, v21
	v_fmac_f32_e32 v34, v18, v18
	v_fmac_f32_e32 v35, v20, v20
	v_add_f32_e32 v34, v34, v35
	v_add_f32_e32 v16, v16, v34
	v_cmp_gt_i32_e32 vcc, s47, v80
	s_and_saveexec_b64 s[12:13], vcc
	s_cbranch_execz .LBB0_1149
	s_nop 1
	v_add_f32_dpp v16, v16, v16 quad_perm:[1,0,3,2] row_mask:0xf bank_mask:0xf
	s_nop 1
	v_add_f32_dpp v16, v16, v16 quad_perm:[2,3,0,1] row_mask:0xf bank_mask:0xf
	s_nop 1
	v_add_f32_dpp v16, v16, v16 row_half_mirror row_mask:0xf bank_mask:0xf
	s_nop 1
	v_add_f32_dpp v16, v16, v16 row_mirror row_mask:0xf bank_mask:0xf
	s_nop 0
	v_readlane_b32 s98, v16, 0
	v_readlane_b32 s99, v16, 16
	v_readlane_b32 s100, v16, 32
	v_readlane_b32 s101, v16, 48
	v_mov_b32_e32 v34, s98
	v_add_f32_e32 v34, s99, v34
	v_mov_b32_e32 v16, s100
	v_add_f32_e32 v16, s101, v16
	v_add_f32_e32 v16, v34, v16
	v_fmamk_f32 v16, v16, 0x3a800000, v231
	v_mul_f32_e32 v34, 0x4b800000, v16
	v_cmp_gt_f32_e32 vcc, s33, v16
	v_ashrrev_i32_e32 v81, 31, v80
	s_nop 0
	v_cndmask_b32_e32 v16, v16, v34, vcc
	v_rsq_f32_e32 v16, v16
	v_lshlrev_b64 v[34:35], 11, v[80:81]
	v_lshl_add_u64 v[34:35], v[78:79], 0, v[34:35]
	v_mul_f32_e32 v36, 0x45800000, v16
	v_cndmask_b32_e32 v16, v16, v36, vcc
	v_mul_f32_e32 v30, v30, v16
	v_mul_f32_e32 v31, v31, v16
	v_mul_f32_e32 v26, v26, v16
	v_mul_f32_e32 v27, v27, v16
	v_mul_f32_e32 v22, v22, v16
	v_mul_f32_e32 v23, v23, v16
	v_mul_f32_e32 v18, v18, v16
	v_mul_f32_e32 v19, v19, v16
	v_mul_f32_e32 v30, v0, v30
	v_mul_f32_e32 v31, v1, v31
	v_mul_f32_e32 v26, v4, v26
	v_mul_f32_e32 v27, v5, v27
	v_mul_f32_e32 v22, v8, v22
	v_mul_f32_e32 v23, v9, v23
	v_mul_f32_e32 v18, v12, v18
	v_mul_f32_e32 v19, v13, v19
	v_cvt_pk_bf16_f32 v30, v30, v31
	v_mul_f32_e32 v31, v32, v16
	v_cvt_pk_bf16_f32 v26, v26, v27
	v_mul_f32_e32 v27, v28, v16
	v_cvt_pk_bf16_f32 v22, v22, v23
	v_mul_f32_e32 v23, v24, v16
	v_cvt_pk_bf16_f32 v18, v18, v19
	v_mul_f32_e32 v19, v20, v16
	v_mul_f32_e32 v31, v2, v31
	v_mul_f32_e32 v32, v33, v16
	v_mul_f32_e32 v27, v6, v27
	v_mul_f32_e32 v28, v29, v16
	v_mul_f32_e32 v23, v10, v23
	v_mul_f32_e32 v24, v25, v16
	v_mul_f32_e32 v19, v14, v19
	v_mul_f32_e32 v16, v21, v16
	v_mul_f32_e32 v32, v3, v32
	v_cvt_pk_bf16_f32 v31, v31, v32
	global_store_dwordx2 v[34:35], v[30:31], off
	v_mul_f32_e32 v28, v7, v28
	v_cvt_pk_bf16_f32 v27, v27, v28
	global_store_dwordx2 v[34:35], v[26:27], off offset:512
	v_mul_f32_e32 v24, v11, v24
	v_cvt_pk_bf16_f32 v23, v23, v24
	global_store_dwordx2 v[34:35], v[22:23], off offset:1024
	v_mul_f32_e32 v16, v15, v16
	v_cvt_pk_bf16_f32 v19, v19, v16
	global_store_dwordx2 v[34:35], v[18:19], off offset:1536
	s_branch .LBB0_1149
